# nt hint also on the prologue's one-pass f32 weight loads
# speedup vs baseline: 1.0607x; 1.0040x over previous
.Lp0_nog:
	s_add_u32 s26, s26, s43
	s_addc_u32 s27, s27, 0
	v_mul_lo_u32 v10, v7, s28
	v_lshl_add_u32 v10, v6, 4, v10
	s_lshl_b32 s29, s28, 3
	global_load_dwordx4 v[16:19], v10, s[26:27] nt
	s_add_u32 s26, s26, s29
	s_addc_u32 s27, s27, 0
	global_load_dwordx4 v[20:23], v10, s[26:27] nt
	s_add_u32 s26, s26, s29
	s_addc_u32 s27, s27, 0
	global_load_dwordx4 v[24:27], v10, s[26:27] nt
	s_add_u32 s26, s26, s29
	s_addc_u32 s27, s27, 0
	global_load_dwordx4 v[28:31], v10, s[26:27] nt
	s_add_u32 s26, s26, s29
	s_addc_u32 s27, s27, 0
	global_load_dwordx4 v[32:35], v10, s[26:27] nt
	s_add_u32 s26, s26, s29
	s_addc_u32 s27, s27, 0
	global_load_dwordx4 v[36:39], v10, s[26:27] nt
	s_add_u32 s26, s26, s29
	s_addc_u32 s27, s27, 0
	global_load_dwordx4 v[40:43], v10, s[26:27] nt
	s_add_u32 s26, s26, s29
	s_addc_u32 s27, s27, 0
	global_load_dwordx4 v[44:47], v10, s[26:27] nt
	s_cmp_eq_u32 s41, 0
	s_cbranch_scc1 .Lp0_nog2
	s_waitcnt vmcnt(8)
	ds_write_b32 v76, v77

.Lp0_fold:
	s_load_dwordx2 s[32:33], s[84:85], 0x18
	s_mov_b32 s41, 0
	s_sub_u32 s40, s39, 0x900
	v_add_u32_e32 v10, s40, v5
	v_lshlrev_b32_e32 v10, 2, v10
	s_lshl_b32 s40, s21, 14
	s_waitcnt lgkmcnt(0)
	s_add_u32 s32, s32, s40
	s_addc_u32 s33, s33, 0
	global_load_dword v98, v10, s[32:33] offset:0
	global_load_dword v99, v10, s[32:33] offset:1024
	global_load_dword v100, v10, s[32:33] offset:2048
	global_load_dword v101, v10, s[32:33] offset:3072
	s_add_u32 s32, s32, 0x1000
	s_addc_u32 s33, s33, 0
	global_load_dword v102, v10, s[32:33] offset:0
	global_load_dword v103, v10, s[32:33] offset:1024
	global_load_dword v104, v10, s[32:33] offset:2048
	global_load_dword v105, v10, s[32:33] offset:3072
	s_add_u32 s32, s32, 0x1000
	s_addc_u32 s33, s33, 0
	global_load_dword v106, v10, s[32:33] offset:0
	global_load_dword v107, v10, s[32:33] offset:1024
	global_load_dword v108, v10, s[32:33] offset:2048
	global_load_dword v109, v10, s[32:33] offset:3072
	s_add_u32 s32, s32, 0x1000
	s_addc_u32 s33, s33, 0
	global_load_dword v110, v10, s[32:33] offset:0
	global_load_dword v111, v10, s[32:33] offset:1024
	global_load_dword v112, v10, s[32:33] offset:2048
	global_load_dword v113, v10, s[32:33] offset:3072
	v_mul_u32_u24_e32 v72, 0x2440, v4
	v_add_u32_e32 v72, 0x1800, v72
	global_load_dwordx4 v[16:19], v72, s[26:27] offset:0 nt
	global_load_dwordx4 v[20:23], v72, s[26:27] offset:16 nt
	global_load_dwordx4 v[24:27], v72, s[26:27] offset:32 nt
	global_load_dwordx4 v[28:31], v72, s[26:27] offset:48 nt
	global_load_dword v114, v13, s[30:31] offset:0
	s_add_u32 s26, s26, s29
	s_addc_u32 s27, s27, 0
	global_load_dwordx4 v[32:35], v72, s[26:27] offset:0 nt
	global_load_dwordx4 v[36:39], v72, s[26:27] offset:16 nt
	global_load_dwordx4 v[40:43], v72, s[26:27] offset:32 nt
	global_load_dwordx4 v[44:47], v72, s[26:27] offset:48 nt
	global_load_dword v115, v13, s[30:31] offset:8
	s_add_u32 s26, s26, s29
	s_addc_u32 s27, s27, 0
	global_load_dwordx4 v[48:51], v72, s[26:27] offset:0 nt
	global_load_dwordx4 v[52:55], v72, s[26:27] offset:16 nt
	global_load_dwordx4 v[56:59], v72, s[26:27] offset:32 nt
	global_load_dwordx4 v[60:63], v72, s[26:27] offset:48 nt
	global_load_dword v116, v13, s[30:31] offset:16
	s_add_u32 s26, s26, s29
	s_addc_u32 s27, s27, 0
	global_load_dwordx4 v[64:67], v72, s[26:27] offset:0 nt
	global_load_dwordx4 v[68:71], v72, s[26:27] offset:16 nt
	global_load_dwordx4 v[90:93], v72, s[26:27] offset:32 nt
	global_load_dwordx4 v[94:97], v72, s[26:27] offset:48 nt
	global_load_dword v117, v13, s[30:31] offset:24
	s_add_u32 s26, s26, s29
	s_addc_u32 s27, s27, 0
	s_waitcnt vmcnt(15)
	v_mul_f32_e32 v118, v16, v98
	v_fmac_f32_e32 v118, v17, v99
	v_fmac_f32_e32 v118, v18, v100
	v_fmac_f32_e32 v118, v19, v101
	v_fmac_f32_e32 v118, v20, v102
	v_fmac_f32_e32 v118, v21, v103
	v_fmac_f32_e32 v118, v22, v104
	v_fmac_f32_e32 v118, v23, v105
	v_fmac_f32_e32 v118, v24, v106
	v_fmac_f32_e32 v118, v25, v107
	v_fmac_f32_e32 v118, v26, v108
	v_fmac_f32_e32 v118, v27, v109
	v_fmac_f32_e32 v118, v28, v110
	v_fmac_f32_e32 v118, v29, v111
	v_fmac_f32_e32 v118, v30, v112
	v_fmac_f32_e32 v118, v31, v113
	v_mul_f32_e32 v118, v114, v118
	ds_write_b32 v78, v118 offset:0
	s_waitcnt vmcnt(10)
	v_mul_f32_e32 v119, v32, v98
	v_fmac_f32_e32 v119, v33, v99
	v_fmac_f32_e32 v119, v34, v100
	v_fmac_f32_e32 v119, v35, v101
	v_fmac_f32_e32 v119, v36, v102
	v_fmac_f32_e32 v119, v37, v103
	v_fmac_f32_e32 v119, v38, v104
	v_fmac_f32_e32 v119, v39, v105
	v_fmac_f32_e32 v119, v40, v106
	v_fmac_f32_e32 v119, v41, v107
	v_fmac_f32_e32 v119, v42, v108
	v_fmac_f32_e32 v119, v43, v109
	v_fmac_f32_e32 v119, v44, v110
	v_fmac_f32_e32 v119, v45, v111
	v_fmac_f32_e32 v119, v46, v112
	v_fmac_f32_e32 v119, v47, v113
	v_mul_f32_e32 v119, v115, v119
	ds_write_b32 v78, v119 offset:264
	s_waitcnt vmcnt(5)
	v_mul_f32_e32 v120, v48, v98
	v_fmac_f32_e32 v120, v49, v99
	v_fmac_f32_e32 v120, v50, v100
	v_fmac_f32_e32 v120, v51, v101
	v_fmac_f32_e32 v120, v52, v102
	v_fmac_f32_e32 v120, v53, v103
	v_fmac_f32_e32 v120, v54, v104
	v_fmac_f32_e32 v120, v55, v105
	v_fmac_f32_e32 v120, v56, v106
	v_fmac_f32_e32 v120, v57, v107
	v_fmac_f32_e32 v120, v58, v108
	v_fmac_f32_e32 v120, v59, v109
	v_fmac_f32_e32 v120, v60, v110
	v_fmac_f32_e32 v120, v61, v111
	v_fmac_f32_e32 v120, v62, v112
	v_fmac_f32_e32 v120, v63, v113
	v_mul_f32_e32 v120, v116, v120
	ds_write_b32 v78, v120 offset:528
	s_waitcnt vmcnt(0)
	v_mul_f32_e32 v121, v64, v98
	v_fmac_f32_e32 v121, v65, v99
	v_fmac_f32_e32 v121, v66, v100
	v_fmac_f32_e32 v121, v67, v101
	v_fmac_f32_e32 v121, v68, v102
	v_fmac_f32_e32 v121, v69, v103
	v_fmac_f32_e32 v121, v70, v104
	v_fmac_f32_e32 v121, v71, v105
	v_fmac_f32_e32 v121, v90, v106
	v_fmac_f32_e32 v121, v91, v107
	v_fmac_f32_e32 v121, v92, v108
	v_fmac_f32_e32 v121, v93, v109
	v_fmac_f32_e32 v121, v94, v110
	v_fmac_f32_e32 v121, v95, v111
	v_fmac_f32_e32 v121, v96, v112
	v_fmac_f32_e32 v121, v97, v113
	v_mul_f32_e32 v121, v117, v121
	ds_write_b32 v78, v121 offset:792
	global_load_dwordx4 v[16:19], v72, s[26:27] offset:0 nt
	global_load_dwordx4 v[20:23], v72, s[26:27] offset:16 nt
	global_load_dwordx4 v[24:27], v72, s[26:27] offset:32 nt
	global_load_dwordx4 v[28:31], v72, s[26:27] offset:48 nt
	global_load_dword v114, v13, s[30:31] offset:32
	s_add_u32 s26, s26, s29
	s_addc_u32 s27, s27, 0
	global_load_dwordx4 v[32:35], v72, s[26:27] offset:0 nt
	global_load_dwordx4 v[36:39], v72, s[26:27] offset:16 nt
	global_load_dwordx4 v[40:43], v72, s[26:27] offset:32 nt
	global_load_dwordx4 v[44:47], v72, s[26:27] offset:48 nt
	global_load_dword v115, v13, s[30:31] offset:40
	s_add_u32 s26, s26, s29
	s_addc_u32 s27, s27, 0
	global_load_dwordx4 v[48:51], v72, s[26:27] offset:0 nt
	global_load_dwordx4 v[52:55], v72, s[26:27] offset:16 nt
	global_load_dwordx4 v[56:59], v72, s[26:27] offset:32 nt
	global_load_dwordx4 v[60:63], v72, s[26:27] offset:48 nt
	global_load_dword v116, v13, s[30:31] offset:48
	s_add_u32 s26, s26, s29
	s_addc_u32 s27, s27, 0
	global_load_dwordx4 v[64:67], v72, s[26:27] offset:0 nt
	global_load_dwordx4 v[68:71], v72, s[26:27] offset:16 nt
	global_load_dwordx4 v[90:93], v72, s[26:27] offset:32 nt
	global_load_dwordx4 v[94:97], v72, s[26:27] offset:48 nt
	global_load_dword v117, v13, s[30:31] offset:56
	s_add_u32 s26, s26, s29
	s_addc_u32 s27, s27, 0
	s_waitcnt vmcnt(15)
	v_mul_f32_e32 v118, v16, v98
	v_fmac_f32_e32 v118, v17, v99
	v_fmac_f32_e32 v118, v18, v100
	v_fmac_f32_e32 v118, v19, v101
	v_fmac_f32_e32 v118, v20, v102
	v_fmac_f32_e32 v118, v21, v103
	v_fmac_f32_e32 v118, v22, v104
	v_fmac_f32_e32 v118, v23, v105
	v_fmac_f32_e32 v118, v24, v106
	v_fmac_f32_e32 v118, v25, v107
	v_fmac_f32_e32 v118, v26, v108
	v_fmac_f32_e32 v118, v27, v109
	v_fmac_f32_e32 v118, v28, v110
	v_fmac_f32_e32 v118, v29, v111
	v_fmac_f32_e32 v118, v30, v112
	v_fmac_f32_e32 v118, v31, v113
	v_mul_f32_e32 v118, v114, v118
	ds_write_b32 v78, v118 offset:1056
	s_waitcnt vmcnt(10)
	v_mul_f32_e32 v119, v32, v98
	v_fmac_f32_e32 v119, v33, v99
	v_fmac_f32_e32 v119, v34, v100
	v_fmac_f32_e32 v119, v35, v101
	v_fmac_f32_e32 v119, v36, v102
	v_fmac_f32_e32 v119, v37, v103
	v_fmac_f32_e32 v119, v38, v104
	v_fmac_f32_e32 v119, v39, v105
	v_fmac_f32_e32 v119, v40, v106
	v_fmac_f32_e32 v119, v41, v107
	v_fmac_f32_e32 v119, v42, v108
	v_fmac_f32_e32 v119, v43, v109
	v_fmac_f32_e32 v119, v44, v110
	v_fmac_f32_e32 v119, v45, v111
	v_fmac_f32_e32 v119, v46, v112
	v_fmac_f32_e32 v119, v47, v113
	v_mul_f32_e32 v119, v115, v119
	ds_write_b32 v78, v119 offset:1320
	s_waitcnt vmcnt(5)
	v_mul_f32_e32 v120, v48, v98
	v_fmac_f32_e32 v120, v49, v99
	v_fmac_f32_e32 v120, v50, v100
	v_fmac_f32_e32 v120, v51, v101
	v_fmac_f32_e32 v120, v52, v102
	v_fmac_f32_e32 v120, v53, v103
	v_fmac_f32_e32 v120, v54, v104
	v_fmac_f32_e32 v120, v55, v105
	v_fmac_f32_e32 v120, v56, v106
	v_fmac_f32_e32 v120, v57, v107
	v_fmac_f32_e32 v120, v58, v108
	v_fmac_f32_e32 v120, v59, v109
	v_fmac_f32_e32 v120, v60, v110
	v_fmac_f32_e32 v120, v61, v111
	v_fmac_f32_e32 v120, v62, v112
	v_fmac_f32_e32 v120, v63, v113
	v_mul_f32_e32 v120, v116, v120
	ds_write_b32 v78, v120 offset:1584
	s_waitcnt vmcnt(0)
	v_mul_f32_e32 v121, v64, v98
	v_fmac_f32_e32 v121, v65, v99
	v_fmac_f32_e32 v121, v66, v100
	v_fmac_f32_e32 v121, v67, v101
	v_fmac_f32_e32 v121, v68, v102
	v_fmac_f32_e32 v121, v69, v103
	v_fmac_f32_e32 v121, v70, v104
	v_fmac_f32_e32 v121, v71, v105
	v_fmac_f32_e32 v121, v90, v106
	v_fmac_f32_e32 v121, v91, v107
	v_fmac_f32_e32 v121, v92, v108
	v_fmac_f32_e32 v121, v93, v109
	v_fmac_f32_e32 v121, v94, v110
	v_fmac_f32_e32 v121, v95, v111
	v_fmac_f32_e32 v121, v96, v112
	v_fmac_f32_e32 v121, v97, v113
	v_mul_f32_e32 v121, v117, v121
	ds_write_b32 v78, v121 offset:1848
	global_load_dwordx4 v[16:19], v72, s[26:27] offset:0 nt
	global_load_dwordx4 v[20:23], v72, s[26:27] offset:16 nt
	global_load_dwordx4 v[24:27], v72, s[26:27] offset:32 nt
	global_load_dwordx4 v[28:31], v72, s[26:27] offset:48 nt
	global_load_dword v114, v13, s[30:31] offset:64
	s_add_u32 s26, s26, s29
	s_addc_u32 s27, s27, 0
	global_load_dwordx4 v[32:35], v72, s[26:27] offset:0 nt
	global_load_dwordx4 v[36:39], v72, s[26:27] offset:16 nt
	global_load_dwordx4 v[40:43], v72, s[26:27] offset:32 nt
	global_load_dwordx4 v[44:47], v72, s[26:27] offset:48 nt
	global_load_dword v115, v13, s[30:31] offset:72
	s_add_u32 s26, s26, s29
	s_addc_u32 s27, s27, 0
	global_load_dwordx4 v[48:51], v72, s[26:27] offset:0 nt
	global_load_dwordx4 v[52:55], v72, s[26:27] offset:16 nt
	global_load_dwordx4 v[56:59], v72, s[26:27] offset:32 nt
	global_load_dwordx4 v[60:63], v72, s[26:27] offset:48 nt
	global_load_dword v116, v13, s[30:31] offset:80
	s_add_u32 s26, s26, s29
	s_addc_u32 s27, s27, 0
	global_load_dwordx4 v[64:67], v72, s[26:27] offset:0 nt
	global_load_dwordx4 v[68:71], v72, s[26:27] offset:16 nt
	global_load_dwordx4 v[90:93], v72, s[26:27] offset:32 nt
	global_load_dwordx4 v[94:97], v72, s[26:27] offset:48 nt
	global_load_dword v117, v13, s[30:31] offset:88
	s_add_u32 s26, s26, s29
	s_addc_u32 s27, s27, 0
	s_waitcnt vmcnt(15)
	v_mul_f32_e32 v118, v16, v98
	v_fmac_f32_e32 v118, v17, v99
	v_fmac_f32_e32 v118, v18, v100
	v_fmac_f32_e32 v118, v19, v101
	v_fmac_f32_e32 v118, v20, v102
	v_fmac_f32_e32 v118, v21, v103
	v_fmac_f32_e32 v118, v22, v104
	v_fmac_f32_e32 v118, v23, v105
	v_fmac_f32_e32 v118, v24, v106
	v_fmac_f32_e32 v118, v25, v107
	v_fmac_f32_e32 v118, v26, v108
	v_fmac_f32_e32 v118, v27, v109
	v_fmac_f32_e32 v118, v28, v110
	v_fmac_f32_e32 v118, v29, v111
	v_fmac_f32_e32 v118, v30, v112
	v_fmac_f32_e32 v118, v31, v113
	v_mul_f32_e32 v118, v114, v118
	ds_write_b32 v78, v118 offset:2112
	s_waitcnt vmcnt(10)
	v_mul_f32_e32 v119, v32, v98
	v_fmac_f32_e32 v119, v33, v99
	v_fmac_f32_e32 v119, v34, v100
	v_fmac_f32_e32 v119, v35, v101
	v_fmac_f32_e32 v119, v36, v102
	v_fmac_f32_e32 v119, v37, v103
	v_fmac_f32_e32 v119, v38, v104
	v_fmac_f32_e32 v119, v39, v105
	v_fmac_f32_e32 v119, v40, v106
	v_fmac_f32_e32 v119, v41, v107
	v_fmac_f32_e32 v119, v42, v108
	v_fmac_f32_e32 v119, v43, v109
	v_fmac_f32_e32 v119, v44, v110
	v_fmac_f32_e32 v119, v45, v111
	v_fmac_f32_e32 v119, v46, v112
	v_fmac_f32_e32 v119, v47, v113
	v_mul_f32_e32 v119, v115, v119
	ds_write_b32 v78, v119 offset:2376
	s_waitcnt vmcnt(5)
	v_mul_f32_e32 v120, v48, v98
	v_fmac_f32_e32 v120, v49, v99
	v_fmac_f32_e32 v120, v50, v100
	v_fmac_f32_e32 v120, v51, v101
	v_fmac_f32_e32 v120, v52, v102
	v_fmac_f32_e32 v120, v53, v103
	v_fmac_f32_e32 v120, v54, v104
	v_fmac_f32_e32 v120, v55, v105
	v_fmac_f32_e32 v120, v56, v106
	v_fmac_f32_e32 v120, v57, v107
	v_fmac_f32_e32 v120, v58, v108
	v_fmac_f32_e32 v120, v59, v109
	v_fmac_f32_e32 v120, v60, v110
	v_fmac_f32_e32 v120, v61, v111
	v_fmac_f32_e32 v120, v62, v112
	v_fmac_f32_e32 v120, v63, v113
	v_mul_f32_e32 v120, v116, v120
	ds_write_b32 v78, v120 offset:2640
	s_waitcnt vmcnt(0)
	v_mul_f32_e32 v121, v64, v98
	v_fmac_f32_e32 v121, v65, v99
	v_fmac_f32_e32 v121, v66, v100
	v_fmac_f32_e32 v121, v67, v101
	v_fmac_f32_e32 v121, v68, v102
	v_fmac_f32_e32 v121, v69, v103
	v_fmac_f32_e32 v121, v70, v104
	v_fmac_f32_e32 v121, v71, v105
	v_fmac_f32_e32 v121, v90, v106
	v_fmac_f32_e32 v121, v91, v107
	v_fmac_f32_e32 v121, v92, v108
	v_fmac_f32_e32 v121, v93, v109
	v_fmac_f32_e32 v121, v94, v110
	v_fmac_f32_e32 v121, v95, v111
	v_fmac_f32_e32 v121, v96, v112
	v_fmac_f32_e32 v121, v97, v113
	v_mul_f32_e32 v121, v117, v121
	ds_write_b32 v78, v121 offset:2904
	global_load_dwordx4 v[16:19], v72, s[26:27] offset:0 nt
	global_load_dwordx4 v[20:23], v72, s[26:27] offset:16 nt
	global_load_dwordx4 v[24:27], v72, s[26:27] offset:32 nt
	global_load_dwordx4 v[28:31], v72, s[26:27] offset:48 nt
	global_load_dword v114, v13, s[30:31] offset:96
	s_add_u32 s26, s26, s29
	s_addc_u32 s27, s27, 0
	global_load_dwordx4 v[32:35], v72, s[26:27] offset:0 nt
	global_load_dwordx4 v[36:39], v72, s[26:27] offset:16 nt
	global_load_dwordx4 v[40:43], v72, s[26:27] offset:32 nt
	global_load_dwordx4 v[44:47], v72, s[26:27] offset:48 nt
	global_load_dword v115, v13, s[30:31] offset:104
	s_add_u32 s26, s26, s29
	s_addc_u32 s27, s27, 0
	global_load_dwordx4 v[48:51], v72, s[26:27] offset:0 nt
	global_load_dwordx4 v[52:55], v72, s[26:27] offset:16 nt
	global_load_dwordx4 v[56:59], v72, s[26:27] offset:32 nt
	global_load_dwordx4 v[60:63], v72, s[26:27] offset:48 nt
	global_load_dword v116, v13, s[30:31] offset:112
	s_add_u32 s26, s26, s29
	s_addc_u32 s27, s27, 0
	global_load_dwordx4 v[64:67], v72, s[26:27] offset:0 nt
	global_load_dwordx4 v[68:71], v72, s[26:27] offset:16 nt
	global_load_dwordx4 v[90:93], v72, s[26:27] offset:32 nt
	global_load_dwordx4 v[94:97], v72, s[26:27] offset:48 nt
	global_load_dword v117, v13, s[30:31] offset:120
	s_add_u32 s26, s26, s29
	s_addc_u32 s27, s27, 0
	s_waitcnt vmcnt(15)
	v_mul_f32_e32 v118, v16, v98
	v_fmac_f32_e32 v118, v17, v99
	v_fmac_f32_e32 v118, v18, v100
	v_fmac_f32_e32 v118, v19, v101
	v_fmac_f32_e32 v118, v20, v102
	v_fmac_f32_e32 v118, v21, v103
	v_fmac_f32_e32 v118, v22, v104
	v_fmac_f32_e32 v118, v23, v105
	v_fmac_f32_e32 v118, v24, v106
	v_fmac_f32_e32 v118, v25, v107
	v_fmac_f32_e32 v118, v26, v108
	v_fmac_f32_e32 v118, v27, v109
	v_fmac_f32_e32 v118, v28, v110
	v_fmac_f32_e32 v118, v29, v111
	v_fmac_f32_e32 v118, v30, v112
	v_fmac_f32_e32 v118, v31, v113
	v_mul_f32_e32 v118, v114, v118
	ds_write_b32 v78, v118 offset:3168
	s_waitcnt vmcnt(10)
	v_mul_f32_e32 v119, v32, v98
	v_fmac_f32_e32 v119, v33, v99
	v_fmac_f32_e32 v119, v34, v100
	v_fmac_f32_e32 v119, v35, v101
	v_fmac_f32_e32 v119, v36, v102
	v_fmac_f32_e32 v119, v37, v103
	v_fmac_f32_e32 v119, v38, v104
	v_fmac_f32_e32 v119, v39, v105
	v_fmac_f32_e32 v119, v40, v106
	v_fmac_f32_e32 v119, v41, v107
	v_fmac_f32_e32 v119, v42, v108
	v_fmac_f32_e32 v119, v43, v109
	v_fmac_f32_e32 v119, v44, v110
	v_fmac_f32_e32 v119, v45, v111
	v_fmac_f32_e32 v119, v46, v112
	v_fmac_f32_e32 v119, v47, v113
	v_mul_f32_e32 v119, v115, v119
	ds_write_b32 v78, v119 offset:3432
	s_waitcnt vmcnt(5)
	v_mul_f32_e32 v120, v48, v98
	v_fmac_f32_e32 v120, v49, v99
	v_fmac_f32_e32 v120, v50, v100
	v_fmac_f32_e32 v120, v51, v101
	v_fmac_f32_e32 v120, v52, v102
	v_fmac_f32_e32 v120, v53, v103
	v_fmac_f32_e32 v120, v54, v104
	v_fmac_f32_e32 v120, v55, v105
	v_fmac_f32_e32 v120, v56, v106
	v_fmac_f32_e32 v120, v57, v107
	v_fmac_f32_e32 v120, v58, v108
	v_fmac_f32_e32 v120, v59, v109
	v_fmac_f32_e32 v120, v60, v110
	v_fmac_f32_e32 v120, v61, v111
	v_fmac_f32_e32 v120, v62, v112
	v_fmac_f32_e32 v120, v63, v113
	v_mul_f32_e32 v120, v116, v120
	ds_write_b32 v78, v120 offset:3696
	s_waitcnt vmcnt(0)
	v_mul_f32_e32 v121, v64, v98
	v_fmac_f32_e32 v121, v65, v99
	v_fmac_f32_e32 v121, v66, v100
	v_fmac_f32_e32 v121, v67, v101
	v_fmac_f32_e32 v121, v68, v102
	v_fmac_f32_e32 v121, v69, v103
	v_fmac_f32_e32 v121, v70, v104
	v_fmac_f32_e32 v121, v71, v105
	v_fmac_f32_e32 v121, v90, v106
	v_fmac_f32_e32 v121, v91, v107
	v_fmac_f32_e32 v121, v92, v108
	v_fmac_f32_e32 v121, v93, v109
	v_fmac_f32_e32 v121, v94, v110
	v_fmac_f32_e32 v121, v95, v111
	v_fmac_f32_e32 v121, v96, v112
	v_fmac_f32_e32 v121, v97, v113
	v_mul_f32_e32 v121, v117, v121
	ds_write_b32 v78, v121 offset:3960
	global_load_dwordx4 v[16:19], v72, s[26:27] offset:0 nt
	global_load_dwordx4 v[20:23], v72, s[26:27] offset:16 nt
	global_load_dwordx4 v[24:27], v72, s[26:27] offset:32 nt
	global_load_dwordx4 v[28:31], v72, s[26:27] offset:48 nt
	global_load_dword v114, v13, s[30:31] offset:128
	s_add_u32 s26, s26, s29
	s_addc_u32 s27, s27, 0
	global_load_dwordx4 v[32:35], v72, s[26:27] offset:0 nt
	global_load_dwordx4 v[36:39], v72, s[26:27] offset:16 nt
	global_load_dwordx4 v[40:43], v72, s[26:27] offset:32 nt
	global_load_dwordx4 v[44:47], v72, s[26:27] offset:48 nt
	global_load_dword v115, v13, s[30:31] offset:136
	s_add_u32 s26, s26, s29
	s_addc_u32 s27, s27, 0
	global_load_dwordx4 v[48:51], v72, s[26:27] offset:0 nt
	global_load_dwordx4 v[52:55], v72, s[26:27] offset:16 nt
	global_load_dwordx4 v[56:59], v72, s[26:27] offset:32 nt
	global_load_dwordx4 v[60:63], v72, s[26:27] offset:48 nt
	global_load_dword v116, v13, s[30:31] offset:144
	s_add_u32 s26, s26, s29
	s_addc_u32 s27, s27, 0
	global_load_dwordx4 v[64:67], v72, s[26:27] offset:0 nt
	global_load_dwordx4 v[68:71], v72, s[26:27] offset:16 nt
	global_load_dwordx4 v[90:93], v72, s[26:27] offset:32 nt
	global_load_dwordx4 v[94:97], v72, s[26:27] offset:48 nt
	global_load_dword v117, v13, s[30:31] offset:152
	s_add_u32 s26, s26, s29
	s_addc_u32 s27, s27, 0
	s_waitcnt vmcnt(15)
	v_mul_f32_e32 v118, v16, v98
	v_fmac_f32_e32 v118, v17, v99
	v_fmac_f32_e32 v118, v18, v100
	v_fmac_f32_e32 v118, v19, v101
	v_fmac_f32_e32 v118, v20, v102
	v_fmac_f32_e32 v118, v21, v103
	v_fmac_f32_e32 v118, v22, v104
	v_fmac_f32_e32 v118, v23, v105
	v_fmac_f32_e32 v118, v24, v106
	v_fmac_f32_e32 v118, v25, v107
	v_fmac_f32_e32 v118, v26, v108
	v_fmac_f32_e32 v118, v27, v109
	v_fmac_f32_e32 v118, v28, v110
	v_fmac_f32_e32 v118, v29, v111
	v_fmac_f32_e32 v118, v30, v112
	v_fmac_f32_e32 v118, v31, v113
	v_mul_f32_e32 v118, v114, v118
	ds_write_b32 v78, v118 offset:4224
	s_waitcnt vmcnt(10)
	v_mul_f32_e32 v119, v32, v98
	v_fmac_f32_e32 v119, v33, v99
	v_fmac_f32_e32 v119, v34, v100
	v_fmac_f32_e32 v119, v35, v101
	v_fmac_f32_e32 v119, v36, v102
	v_fmac_f32_e32 v119, v37, v103
	v_fmac_f32_e32 v119, v38, v104
	v_fmac_f32_e32 v119, v39, v105
	v_fmac_f32_e32 v119, v40, v106
	v_fmac_f32_e32 v119, v41, v107
	v_fmac_f32_e32 v119, v42, v108
	v_fmac_f32_e32 v119, v43, v109
	v_fmac_f32_e32 v119, v44, v110
	v_fmac_f32_e32 v119, v45, v111
	v_fmac_f32_e32 v119, v46, v112
	v_fmac_f32_e32 v119, v47, v113
	v_mul_f32_e32 v119, v115, v119
	ds_write_b32 v78, v119 offset:4488
	s_waitcnt vmcnt(5)
	v_mul_f32_e32 v120, v48, v98
	v_fmac_f32_e32 v120, v49, v99
	v_fmac_f32_e32 v120, v50, v100
	v_fmac_f32_e32 v120, v51, v101
	v_fmac_f32_e32 v120, v52, v102
	v_fmac_f32_e32 v120, v53, v103
	v_fmac_f32_e32 v120, v54, v104
	v_fmac_f32_e32 v120, v55, v105
	v_fmac_f32_e32 v120, v56, v106
	v_fmac_f32_e32 v120, v57, v107
	v_fmac_f32_e32 v120, v58, v108
	v_fmac_f32_e32 v120, v59, v109
	v_fmac_f32_e32 v120, v60, v110
	v_fmac_f32_e32 v120, v61, v111
	v_fmac_f32_e32 v120, v62, v112
	v_fmac_f32_e32 v120, v63, v113
	v_mul_f32_e32 v120, v116, v120
	ds_write_b32 v78, v120 offset:4752
	s_waitcnt vmcnt(0)
	v_mul_f32_e32 v121, v64, v98
	v_fmac_f32_e32 v121, v65, v99
	v_fmac_f32_e32 v121, v66, v100
	v_fmac_f32_e32 v121, v67, v101
	v_fmac_f32_e32 v121, v68, v102
	v_fmac_f32_e32 v121, v69, v103
	v_fmac_f32_e32 v121, v70, v104
	v_fmac_f32_e32 v121, v71, v105
	v_fmac_f32_e32 v121, v90, v106
	v_fmac_f32_e32 v121, v91, v107
	v_fmac_f32_e32 v121, v92, v108
	v_fmac_f32_e32 v121, v93, v109
	v_fmac_f32_e32 v121, v94, v110
	v_fmac_f32_e32 v121, v95, v111
	v_fmac_f32_e32 v121, v96, v112
	v_fmac_f32_e32 v121, v97, v113
	v_mul_f32_e32 v121, v117, v121
	ds_write_b32 v78, v121 offset:5016
	global_load_dwordx4 v[16:19], v72, s[26:27] offset:0 nt
	global_load_dwordx4 v[20:23], v72, s[26:27] offset:16 nt
	global_load_dwordx4 v[24:27], v72, s[26:27] offset:32 nt
	global_load_dwordx4 v[28:31], v72, s[26:27] offset:48 nt
	global_load_dword v114, v13, s[30:31] offset:160
	s_add_u32 s26, s26, s29
	s_addc_u32 s27, s27, 0
	global_load_dwordx4 v[32:35], v72, s[26:27] offset:0 nt
	global_load_dwordx4 v[36:39], v72, s[26:27] offset:16 nt
	global_load_dwordx4 v[40:43], v72, s[26:27] offset:32 nt
	global_load_dwordx4 v[44:47], v72, s[26:27] offset:48 nt
	global_load_dword v115, v13, s[30:31] offset:168
	s_add_u32 s26, s26, s29
	s_addc_u32 s27, s27, 0
	global_load_dwordx4 v[48:51], v72, s[26:27] offset:0 nt
	global_load_dwordx4 v[52:55], v72, s[26:27] offset:16 nt
	global_load_dwordx4 v[56:59], v72, s[26:27] offset:32 nt
	global_load_dwordx4 v[60:63], v72, s[26:27] offset:48 nt
	global_load_dword v116, v13, s[30:31] offset:176
	s_add_u32 s26, s26, s29
	s_addc_u32 s27, s27, 0
	global_load_dwordx4 v[64:67], v72, s[26:27] offset:0 nt
	global_load_dwordx4 v[68:71], v72, s[26:27] offset:16 nt
	global_load_dwordx4 v[90:93], v72, s[26:27] offset:32 nt
	global_load_dwordx4 v[94:97], v72, s[26:27] offset:48 nt
	global_load_dword v117, v13, s[30:31] offset:184
	s_add_u32 s26, s26, s29
	s_addc_u32 s27, s27, 0
	s_waitcnt vmcnt(15)
	v_mul_f32_e32 v118, v16, v98
	v_fmac_f32_e32 v118, v17, v99
	v_fmac_f32_e32 v118, v18, v100
	v_fmac_f32_e32 v118, v19, v101
	v_fmac_f32_e32 v118, v20, v102
	v_fmac_f32_e32 v118, v21, v103
	v_fmac_f32_e32 v118, v22, v104
	v_fmac_f32_e32 v118, v23, v105
	v_fmac_f32_e32 v118, v24, v106
	v_fmac_f32_e32 v118, v25, v107
	v_fmac_f32_e32 v118, v26, v108
	v_fmac_f32_e32 v118, v27, v109
	v_fmac_f32_e32 v118, v28, v110
	v_fmac_f32_e32 v118, v29, v111
	v_fmac_f32_e32 v118, v30, v112
	v_fmac_f32_e32 v118, v31, v113
	v_mul_f32_e32 v118, v114, v118
	ds_write_b32 v78, v118 offset:5280
	s_waitcnt vmcnt(10)
	v_mul_f32_e32 v119, v32, v98
	v_fmac_f32_e32 v119, v33, v99
	v_fmac_f32_e32 v119, v34, v100
	v_fmac_f32_e32 v119, v35, v101
	v_fmac_f32_e32 v119, v36, v102
	v_fmac_f32_e32 v119, v37, v103
	v_fmac_f32_e32 v119, v38, v104
	v_fmac_f32_e32 v119, v39, v105
	v_fmac_f32_e32 v119, v40, v106
	v_fmac_f32_e32 v119, v41, v107
	v_fmac_f32_e32 v119, v42, v108
	v_fmac_f32_e32 v119, v43, v109
	v_fmac_f32_e32 v119, v44, v110
	v_fmac_f32_e32 v119, v45, v111
	v_fmac_f32_e32 v119, v46, v112
	v_fmac_f32_e32 v119, v47, v113
	v_mul_f32_e32 v119, v115, v119
	ds_write_b32 v78, v119 offset:5544
	s_waitcnt vmcnt(5)
	v_mul_f32_e32 v120, v48, v98
	v_fmac_f32_e32 v120, v49, v99
	v_fmac_f32_e32 v120, v50, v100
	v_fmac_f32_e32 v120, v51, v101
	v_fmac_f32_e32 v120, v52, v102
	v_fmac_f32_e32 v120, v53, v103
	v_fmac_f32_e32 v120, v54, v104
	v_fmac_f32_e32 v120, v55, v105
	v_fmac_f32_e32 v120, v56, v106
	v_fmac_f32_e32 v120, v57, v107
	v_fmac_f32_e32 v120, v58, v108
	v_fmac_f32_e32 v120, v59, v109
	v_fmac_f32_e32 v120, v60, v110
	v_fmac_f32_e32 v120, v61, v111
	v_fmac_f32_e32 v120, v62, v112
	v_fmac_f32_e32 v120, v63, v113
	v_mul_f32_e32 v120, v116, v120
	ds_write_b32 v78, v120 offset:5808
	s_waitcnt vmcnt(0)
	v_mul_f32_e32 v121, v64, v98
	v_fmac_f32_e32 v121, v65, v99
	v_fmac_f32_e32 v121, v66, v100
	v_fmac_f32_e32 v121, v67, v101
	v_fmac_f32_e32 v121, v68, v102
	v_fmac_f32_e32 v121, v69, v103
	v_fmac_f32_e32 v121, v70, v104
	v_fmac_f32_e32 v121, v71, v105
	v_fmac_f32_e32 v121, v90, v106
	v_fmac_f32_e32 v121, v91, v107
	v_fmac_f32_e32 v121, v92, v108
	v_fmac_f32_e32 v121, v93, v109
	v_fmac_f32_e32 v121, v94, v110
	v_fmac_f32_e32 v121, v95, v111
	v_fmac_f32_e32 v121, v96, v112
	v_fmac_f32_e32 v121, v97, v113
	v_mul_f32_e32 v121, v117, v121
	ds_write_b32 v78, v121 offset:6072
	global_load_dwordx4 v[16:19], v72, s[26:27] offset:0 nt
	global_load_dwordx4 v[20:23], v72, s[26:27] offset:16 nt
	global_load_dwordx4 v[24:27], v72, s[26:27] offset:32 nt
	global_load_dwordx4 v[28:31], v72, s[26:27] offset:48 nt
	global_load_dword v114, v13, s[30:31] offset:192
	s_add_u32 s26, s26, s29
	s_addc_u32 s27, s27, 0
	global_load_dwordx4 v[32:35], v72, s[26:27] offset:0 nt
	global_load_dwordx4 v[36:39], v72, s[26:27] offset:16 nt
	global_load_dwordx4 v[40:43], v72, s[26:27] offset:32 nt
	global_load_dwordx4 v[44:47], v72, s[26:27] offset:48 nt
	global_load_dword v115, v13, s[30:31] offset:200
	s_add_u32 s26, s26, s29
	s_addc_u32 s27, s27, 0
	global_load_dwordx4 v[48:51], v72, s[26:27] offset:0 nt
	global_load_dwordx4 v[52:55], v72, s[26:27] offset:16 nt
	global_load_dwordx4 v[56:59], v72, s[26:27] offset:32 nt
	global_load_dwordx4 v[60:63], v72, s[26:27] offset:48 nt
	global_load_dword v116, v13, s[30:31] offset:208
	s_add_u32 s26, s26, s29
	s_addc_u32 s27, s27, 0
	global_load_dwordx4 v[64:67], v72, s[26:27] offset:0 nt
	global_load_dwordx4 v[68:71], v72, s[26:27] offset:16 nt
	global_load_dwordx4 v[90:93], v72, s[26:27] offset:32 nt
	global_load_dwordx4 v[94:97], v72, s[26:27] offset:48 nt
	global_load_dword v117, v13, s[30:31] offset:216
	s_add_u32 s26, s26, s29
	s_addc_u32 s27, s27, 0
	s_waitcnt vmcnt(15)
	v_mul_f32_e32 v118, v16, v98
	v_fmac_f32_e32 v118, v17, v99
	v_fmac_f32_e32 v118, v18, v100
	v_fmac_f32_e32 v118, v19, v101
	v_fmac_f32_e32 v118, v20, v102
	v_fmac_f32_e32 v118, v21, v103
	v_fmac_f32_e32 v118, v22, v104
	v_fmac_f32_e32 v118, v23, v105
	v_fmac_f32_e32 v118, v24, v106
	v_fmac_f32_e32 v118, v25, v107
	v_fmac_f32_e32 v118, v26, v108
	v_fmac_f32_e32 v118, v27, v109
	v_fmac_f32_e32 v118, v28, v110
	v_fmac_f32_e32 v118, v29, v111
	v_fmac_f32_e32 v118, v30, v112
	v_fmac_f32_e32 v118, v31, v113
	v_mul_f32_e32 v118, v114, v118
	ds_write_b32 v78, v118 offset:6336
	s_waitcnt vmcnt(10)
	v_mul_f32_e32 v119, v32, v98
	v_fmac_f32_e32 v119, v33, v99
	v_fmac_f32_e32 v119, v34, v100
	v_fmac_f32_e32 v119, v35, v101
	v_fmac_f32_e32 v119, v36, v102
	v_fmac_f32_e32 v119, v37, v103
	v_fmac_f32_e32 v119, v38, v104
	v_fmac_f32_e32 v119, v39, v105
	v_fmac_f32_e32 v119, v40, v106
	v_fmac_f32_e32 v119, v41, v107
	v_fmac_f32_e32 v119, v42, v108
	v_fmac_f32_e32 v119, v43, v109
	v_fmac_f32_e32 v119, v44, v110
	v_fmac_f32_e32 v119, v45, v111
	v_fmac_f32_e32 v119, v46, v112
	v_fmac_f32_e32 v119, v47, v113
	v_mul_f32_e32 v119, v115, v119
	ds_write_b32 v78, v119 offset:6600
	s_waitcnt vmcnt(5)
	v_mul_f32_e32 v120, v48, v98
	v_fmac_f32_e32 v120, v49, v99
	v_fmac_f32_e32 v120, v50, v100
	v_fmac_f32_e32 v120, v51, v101
	v_fmac_f32_e32 v120, v52, v102
	v_fmac_f32_e32 v120, v53, v103
	v_fmac_f32_e32 v120, v54, v104
	v_fmac_f32_e32 v120, v55, v105
	v_fmac_f32_e32 v120, v56, v106
	v_fmac_f32_e32 v120, v57, v107
	v_fmac_f32_e32 v120, v58, v108
	v_fmac_f32_e32 v120, v59, v109
	v_fmac_f32_e32 v120, v60, v110
	v_fmac_f32_e32 v120, v61, v111
	v_fmac_f32_e32 v120, v62, v112
	v_fmac_f32_e32 v120, v63, v113
	v_mul_f32_e32 v120, v116, v120
	ds_write_b32 v78, v120 offset:6864
	s_waitcnt vmcnt(0)
	v_mul_f32_e32 v121, v64, v98
	v_fmac_f32_e32 v121, v65, v99
	v_fmac_f32_e32 v121, v66, v100
	v_fmac_f32_e32 v121, v67, v101
	v_fmac_f32_e32 v121, v68, v102
	v_fmac_f32_e32 v121, v69, v103
	v_fmac_f32_e32 v121, v70, v104
	v_fmac_f32_e32 v121, v71, v105
	v_fmac_f32_e32 v121, v90, v106
	v_fmac_f32_e32 v121, v91, v107
	v_fmac_f32_e32 v121, v92, v108
	v_fmac_f32_e32 v121, v93, v109
	v_fmac_f32_e32 v121, v94, v110
	v_fmac_f32_e32 v121, v95, v111
	v_fmac_f32_e32 v121, v96, v112
	v_fmac_f32_e32 v121, v97, v113
	v_mul_f32_e32 v121, v117, v121
	ds_write_b32 v78, v121 offset:7128
	global_load_dwordx4 v[16:19], v72, s[26:27] offset:0 nt
	global_load_dwordx4 v[20:23], v72, s[26:27] offset:16 nt
	global_load_dwordx4 v[24:27], v72, s[26:27] offset:32 nt
	global_load_dwordx4 v[28:31], v72, s[26:27] offset:48 nt
	global_load_dword v114, v13, s[30:31] offset:224
	s_add_u32 s26, s26, s29
	s_addc_u32 s27, s27, 0
	global_load_dwordx4 v[32:35], v72, s[26:27] offset:0 nt
	global_load_dwordx4 v[36:39], v72, s[26:27] offset:16 nt
	global_load_dwordx4 v[40:43], v72, s[26:27] offset:32 nt
	global_load_dwordx4 v[44:47], v72, s[26:27] offset:48 nt
	global_load_dword v115, v13, s[30:31] offset:232
	s_add_u32 s26, s26, s29
	s_addc_u32 s27, s27, 0
	global_load_dwordx4 v[48:51], v72, s[26:27] offset:0 nt
	global_load_dwordx4 v[52:55], v72, s[26:27] offset:16 nt
	global_load_dwordx4 v[56:59], v72, s[26:27] offset:32 nt
	global_load_dwordx4 v[60:63], v72, s[26:27] offset:48 nt
	global_load_dword v116, v13, s[30:31] offset:240
	s_add_u32 s26, s26, s29
	s_addc_u32 s27, s27, 0
	global_load_dwordx4 v[64:67], v72, s[26:27] offset:0 nt
	global_load_dwordx4 v[68:71], v72, s[26:27] offset:16 nt
	global_load_dwordx4 v[90:93], v72, s[26:27] offset:32 nt
	global_load_dwordx4 v[94:97], v72, s[26:27] offset:48 nt
	global_load_dword v117, v13, s[30:31] offset:248
	s_add_u32 s26, s26, s29
	s_addc_u32 s27, s27, 0
	s_waitcnt vmcnt(15)
	v_mul_f32_e32 v118, v16, v98
	v_fmac_f32_e32 v118, v17, v99
	v_fmac_f32_e32 v118, v18, v100
	v_fmac_f32_e32 v118, v19, v101
	v_fmac_f32_e32 v118, v20, v102
	v_fmac_f32_e32 v118, v21, v103
	v_fmac_f32_e32 v118, v22, v104
	v_fmac_f32_e32 v118, v23, v105
	v_fmac_f32_e32 v118, v24, v106
	v_fmac_f32_e32 v118, v25, v107
	v_fmac_f32_e32 v118, v26, v108
	v_fmac_f32_e32 v118, v27, v109
	v_fmac_f32_e32 v118, v28, v110
	v_fmac_f32_e32 v118, v29, v111
	v_fmac_f32_e32 v118, v30, v112
	v_fmac_f32_e32 v118, v31, v113
	v_mul_f32_e32 v118, v114, v118
	ds_write_b32 v78, v118 offset:7392
	s_waitcnt vmcnt(10)
	v_mul_f32_e32 v119, v32, v98
	v_fmac_f32_e32 v119, v33, v99
	v_fmac_f32_e32 v119, v34, v100
	v_fmac_f32_e32 v119, v35, v101
	v_fmac_f32_e32 v119, v36, v102
	v_fmac_f32_e32 v119, v37, v103
	v_fmac_f32_e32 v119, v38, v104
	v_fmac_f32_e32 v119, v39, v105
	v_fmac_f32_e32 v119, v40, v106
	v_fmac_f32_e32 v119, v41, v107
	v_fmac_f32_e32 v119, v42, v108
	v_fmac_f32_e32 v119, v43, v109
	v_fmac_f32_e32 v119, v44, v110
	v_fmac_f32_e32 v119, v45, v111
	v_fmac_f32_e32 v119, v46, v112
	v_fmac_f32_e32 v119, v47, v113
	v_mul_f32_e32 v119, v115, v119
	ds_write_b32 v78, v119 offset:7656
	s_waitcnt vmcnt(5)
	v_mul_f32_e32 v120, v48, v98
	v_fmac_f32_e32 v120, v49, v99
	v_fmac_f32_e32 v120, v50, v100
	v_fmac_f32_e32 v120, v51, v101
	v_fmac_f32_e32 v120, v52, v102
	v_fmac_f32_e32 v120, v53, v103
	v_fmac_f32_e32 v120, v54, v104
	v_fmac_f32_e32 v120, v55, v105
	v_fmac_f32_e32 v120, v56, v106
	v_fmac_f32_e32 v120, v57, v107
	v_fmac_f32_e32 v120, v58, v108
	v_fmac_f32_e32 v120, v59, v109
	v_fmac_f32_e32 v120, v60, v110
	v_fmac_f32_e32 v120, v61, v111
	v_fmac_f32_e32 v120, v62, v112
	v_fmac_f32_e32 v120, v63, v113
	v_mul_f32_e32 v120, v116, v120
	ds_write_b32 v78, v120 offset:7920
	s_waitcnt vmcnt(0)
	v_mul_f32_e32 v121, v64, v98
	v_fmac_f32_e32 v121, v65, v99
	v_fmac_f32_e32 v121, v66, v100
	v_fmac_f32_e32 v121, v67, v101
	v_fmac_f32_e32 v121, v68, v102
	v_fmac_f32_e32 v121, v69, v103
	v_fmac_f32_e32 v121, v70, v104
	v_fmac_f32_e32 v121, v71, v105
	v_fmac_f32_e32 v121, v90, v106
	v_fmac_f32_e32 v121, v91, v107
	v_fmac_f32_e32 v121, v92, v108
	v_fmac_f32_e32 v121, v93, v109
	v_fmac_f32_e32 v121, v94, v110
	v_fmac_f32_e32 v121, v95, v111
	v_fmac_f32_e32 v121, v96, v112
	v_fmac_f32_e32 v121, v97, v113
	v_mul_f32_e32 v121, v117, v121
	ds_write_b32 v78, v121 offset:8184
